# loader segments: remaining m0-hazard nops filled with address adds / a ds_read / k counter, two dead salu removed per loop
# baseline (speedup 1.0000x reference)
; #define G_STAGE(bufoff, gbase) do { _Pragma("unroll") for (int _i = 0; _i < 2; ++_i) \
;         __builtin_amdgcn_global_load_lds((const unsigned*)((const char*)(gbase) + voff[_i]), (LAS unsigned*)(lds + (bufoff) + ldsw + _i * 8192), 16, 0, 0); } while (0)
; #define G_LDA(dst, b, h) do { _Pragma("unroll") for (int m = 0; m < 4; ++m) _Pragma("unroll") for (int k = 0; k < 2; ++k) dst[m][k] = *(const LAS bf16x8*)(lds + G_SA(b, h) + aoff + m * 2048 + k * 1024); } while (0)
; #define G_LDB(dst, b, h) do { _Pragma("unroll") for (int n = 0; n < 2; ++n) _Pragma("unroll") for (int k = 0; k < 2; ++k) dst[n][k] = *(const LAS bf16x8*)(lds + G_SB(b, h) + boff + n * 2048 + k * 1024); } while (0)
; #define G_MMA(ai, bj, At, Bt) do { __builtin_amdgcn_s_setprio(1); _Pragma("unroll") for (int m = 0; m < 4; ++m) _Pragma("unroll") for (int n = 0; n < 2; ++n) _Pragma("unroll") for (int k = 0; k < 2; ++k) \
;         acc[ai][bj][m][n] = MFMA16(Bt[n][k], At[m][k], acc[ai][bj][m][n]); __builtin_amdgcn_s_setprio(0); } while (0)
; #define G_WAIT_V(n) asm volatile("s_waitcnt vmcnt(" #n ")" ::: "memory")
; #define G_WAIT_L(n) asm volatile("s_waitcnt lgkmcnt(" #n ")" ::: "memory")
; #define G_BAR __builtin_amdgcn_s_barrier()
; #define G_SCHED __builtin_amdgcn_sched_barrier(0)
; template <class Epi>
; __device__ __forceinline__ void gemm_phase(LAS unsigned char* lds, const bf16_t* Ag, const bf16_t* Btg, const int K, const int nM, const int nN, const Epi& E) {
;     ...
;             G_LDB(B0, 0, 0); G_SCHED; G_LDA(At, 0, 0); G_STAGE(G_SA(1, 1), a1 + hstep);
;             G_WAIT_L(8); G_BAR; G_WAIT_L(0); G_MMA(0, 0, At, B0); G_BAR; G_SCHED;
;             G_LDB(B1, 0, 1); G_STAGE(G_SB(0, 0), b2);
;             G_BAR; G_WAIT_L(0); G_MMA(0, 1, At, B1); G_BAR;
;             G_LDA(At, 0, 1); G_STAGE(G_SA(0, 0), a2);
;             G_BAR; G_WAIT_L(0); G_MMA(1, 0, At, B0); G_BAR; G_SCHED;
;             G_STAGE(G_SB(0, 1), b2 + hstep);
;             G_WAIT_V(6); G_BAR; G_MMA(1, 1, At, B1); G_BAR;
.LmainW_78:
	ds_read_b128 v[124:127], v217
	ds_read_b128 v[128:131], v217 offset:1024
	ds_read_b128 v[132:135], v217 offset:2048
	ds_read_b128 v[136:139], v217 offset:3072
	s_add_i32 m0, s58, 0xc000
	ds_read_b128 v[140:143], v186
	ds_read_b128 v[148:151], v186 offset:1024
	ds_read_b128 v[152:155], v186 offset:2048
	ds_read_b128 v[156:159], v186 offset:3072
	ds_read_b128 v[188:191], v186 offset:4096
	ds_read_b128 v[192:195], v186 offset:5120
	ds_read_b128 v[222:225], v186 offset:6144
	global_load_lds_dwordx4 v170, s[50:51]
	s_add_i32 m0, s58, 0xe000
	ds_read_b128 v[226:229], v186 offset:7168
	global_load_lds_dwordx4 v168, s[50:51]
	s_waitcnt lgkmcnt(8)
	s_barrier
	s_waitcnt lgkmcnt(0)
	s_waitcnt lgkmcnt(0)
	v_mfma_f32_16x16x32_bf16 v[164:167], v[124:127], v[140:143], v[164:167]
	v_mfma_f32_16x16x32_bf16 v[160:163], v[132:135], v[140:143], v[160:163]
	v_mfma_f32_16x16x32_bf16 v[116:119], v[124:127], v[152:155], v[116:119]
	v_mfma_f32_16x16x32_bf16 v[112:115], v[132:135], v[152:155], v[112:115]
	v_mfma_f32_16x16x32_bf16 v[100:103], v[124:127], v[188:191], v[100:103]
	v_mfma_f32_16x16x32_bf16 v[96:99], v[132:135], v[188:191], v[96:99]
	v_mfma_f32_16x16x32_bf16 v[84:87], v[124:127], v[222:225], v[84:87]
	v_mfma_f32_16x16x32_bf16 v[80:83], v[132:135], v[222:225], v[80:83]
	v_mfma_f32_16x16x32_bf16 v[164:167], v[128:131], v[148:151], v[164:167]
	v_mfma_f32_16x16x32_bf16 v[160:163], v[136:139], v[148:151], v[160:163]
	v_mfma_f32_16x16x32_bf16 v[116:119], v[128:131], v[156:159], v[116:119]
	v_mfma_f32_16x16x32_bf16 v[112:115], v[136:139], v[156:159], v[112:115]
	v_mfma_f32_16x16x32_bf16 v[100:103], v[128:131], v[192:195], v[100:103]
	v_mfma_f32_16x16x32_bf16 v[96:99], v[136:139], v[192:195], v[96:99]
	v_mfma_f32_16x16x32_bf16 v[84:87], v[128:131], v[226:229], v[84:87]
	v_mfma_f32_16x16x32_bf16 v[80:83], v[136:139], v[226:229], v[80:83]
	s_barrier
	ds_read_b128 v[230:233], v217 offset:16384
	ds_read_b128 v[234:237], v217 offset:17408
	s_add_i32 m0, s57, 0x10000
	ds_read_b128 v[238:241], v217 offset:18432
	global_load_lds_dwordx4 v0, s[52:53]
	s_add_i32 m0, s57, 0x12000
	ds_read_b128 v[242:245], v217 offset:19456
	global_load_lds_dwordx4 v2, s[52:53]
	s_barrier
	s_waitcnt lgkmcnt(0)
	s_waitcnt lgkmcnt(0)
	v_mfma_f32_16x16x32_bf16 v[144:147], v[230:233], v[140:143], v[144:147]
	v_mfma_f32_16x16x32_bf16 v[120:123], v[238:241], v[140:143], v[120:123]
	v_mfma_f32_16x16x32_bf16 v[108:111], v[230:233], v[152:155], v[108:111]
	v_mfma_f32_16x16x32_bf16 v[104:107], v[238:241], v[152:155], v[104:107]
	v_mfma_f32_16x16x32_bf16 v[92:95], v[230:233], v[188:191], v[92:95]
	v_mfma_f32_16x16x32_bf16 v[88:91], v[238:241], v[188:191], v[88:91]
	v_mfma_f32_16x16x32_bf16 v[76:79], v[230:233], v[222:225], v[76:79]
	v_mfma_f32_16x16x32_bf16 v[72:75], v[238:241], v[222:225], v[72:75]
	v_mfma_f32_16x16x32_bf16 v[144:147], v[234:237], v[148:151], v[144:147]
	v_mfma_f32_16x16x32_bf16 v[120:123], v[242:245], v[148:151], v[120:123]
	v_mfma_f32_16x16x32_bf16 v[108:111], v[234:237], v[156:159], v[108:111]
	v_mfma_f32_16x16x32_bf16 v[104:107], v[242:245], v[156:159], v[104:107]
	v_mfma_f32_16x16x32_bf16 v[92:95], v[234:237], v[192:195], v[92:95]
	v_mfma_f32_16x16x32_bf16 v[88:91], v[242:245], v[192:195], v[88:91]
	v_mfma_f32_16x16x32_bf16 v[76:79], v[234:237], v[226:229], v[76:79]
	v_mfma_f32_16x16x32_bf16 v[72:75], v[242:245], v[226:229], v[72:75]
	s_mov_b32 m0, s58
	s_barrier
	ds_read_b128 v[140:143], v186 offset:16384
	ds_read_b128 v[148:151], v186 offset:17408
	ds_read_b128 v[152:155], v186 offset:18432
	ds_read_b128 v[156:159], v186 offset:19456
	ds_read_b128 v[188:191], v186 offset:20480
	ds_read_b128 v[192:195], v186 offset:21504
	ds_read_b128 v[222:225], v186 offset:22528
	global_load_lds_dwordx4 v0, s[54:55]
	s_mov_b32 m0, s59
	ds_read_b128 v[226:229], v186 offset:23552
	global_load_lds_dwordx4 v2, s[54:55]
	s_barrier
	s_waitcnt lgkmcnt(0)
	s_waitcnt lgkmcnt(0)
	v_mfma_f32_16x16x32_bf16 v[60:63], v[124:127], v[140:143], v[60:63]
	v_mfma_f32_16x16x32_bf16 v[56:59], v[132:135], v[140:143], v[56:59]
	v_mfma_f32_16x16x32_bf16 v[44:47], v[124:127], v[152:155], v[44:47]
	v_mfma_f32_16x16x32_bf16 v[40:43], v[132:135], v[152:155], v[40:43]
	v_mfma_f32_16x16x32_bf16 v[28:31], v[124:127], v[188:191], v[28:31]
	v_mfma_f32_16x16x32_bf16 v[24:27], v[132:135], v[188:191], v[24:27]
	v_mfma_f32_16x16x32_bf16 v[12:15], v[124:127], v[222:225], v[12:15]
	v_mfma_f32_16x16x32_bf16 v[8:11], v[132:135], v[222:225], v[8:11]
	v_mfma_f32_16x16x32_bf16 v[60:63], v[128:131], v[148:151], v[60:63]
	v_mfma_f32_16x16x32_bf16 v[56:59], v[136:139], v[148:151], v[56:59]
	v_mfma_f32_16x16x32_bf16 v[44:47], v[128:131], v[156:159], v[44:47]
	v_mfma_f32_16x16x32_bf16 v[40:43], v[136:139], v[156:159], v[40:43]
	v_mfma_f32_16x16x32_bf16 v[28:31], v[128:131], v[192:195], v[28:31]
	v_mfma_f32_16x16x32_bf16 v[24:27], v[136:139], v[192:195], v[24:27]
	v_mfma_f32_16x16x32_bf16 v[12:15], v[128:131], v[226:229], v[12:15]
	v_mfma_f32_16x16x32_bf16 v[8:11], v[136:139], v[226:229], v[8:11]
	s_barrier
	s_add_i32 m0, s57, 0x14000
	s_add_u32 s74, s52, 0x40000
	s_addc_u32 s75, s53, 0
	global_load_lds_dwordx4 v0, s[74:75]
	s_add_i32 m0, s57, 0x16000
	s_add_u32 s54, s54, 0x40000
	s_addc_u32 s55, s55, 0
	global_load_lds_dwordx4 v2, s[74:75]
	s_waitcnt vmcnt(6)
	s_barrier
; #define G_STAGE(bufoff, gbase) do { _Pragma("unroll") for (int _i = 0; _i < 2; ++_i) \
;         __builtin_amdgcn_global_load_lds((const unsigned*)((const char*)(gbase) + voff[_i]), (LAS unsigned*)(lds + (bufoff) + ldsw + _i * 8192), 16, 0, 0); } while (0)
; #define G_LDA(dst, b, h) do { _Pragma("unroll") for (int m = 0; m < 4; ++m) _Pragma("unroll") for (int k = 0; k < 2; ++k) dst[m][k] = *(const LAS bf16x8*)(lds + G_SA(b, h) + aoff + m * 2048 + k * 1024); } while (0)
; #define G_LDB(dst, b, h) do { _Pragma("unroll") for (int n = 0; n < 2; ++n) _Pragma("unroll") for (int k = 0; k < 2; ++k) dst[n][k] = *(const LAS bf16x8*)(lds + G_SB(b, h) + boff + n * 2048 + k * 1024); } while (0)
; #define G_MMA(ai, bj, At, Bt) do { __builtin_amdgcn_s_setprio(1); _Pragma("unroll") for (int m = 0; m < 4; ++m) _Pragma("unroll") for (int n = 0; n < 2; ++n) _Pragma("unroll") for (int k = 0; k < 2; ++k) \
;         acc[ai][bj][m][n] = MFMA16(Bt[n][k], At[m][k], acc[ai][bj][m][n]); __builtin_amdgcn_s_setprio(0); } while (0)
; #define G_WAIT_V(n) asm volatile("s_waitcnt vmcnt(" #n ")" ::: "memory")
; #define G_WAIT_L(n) asm volatile("s_waitcnt lgkmcnt(" #n ")" ::: "memory")
; #define G_BAR __builtin_amdgcn_s_barrier()
; #define G_SCHED __builtin_amdgcn_sched_barrier(0)
; template <class Epi>
; __device__ __forceinline__ void gemm_phase(LAS unsigned char* lds, const bf16_t* Ag, const bf16_t* Btg, const int K, const int nM, const int nN, const Epi& E) {
;     ...
;         for (int t = 0; t < nt; t += 2) {
;             const bool last = (t == nt - 2);
;             const char* a1 = cA + (size_t)(t + 1) * kstep;
;             const char* a2 = last ? nA : cA + (size_t)(t + 2) * kstep; const char* b2 = last ? nB : cB + (size_t)(t + 2) * kstep;
;             const char* a3 = a2 + kstep; const char* b3 = b2 + kstep;
;     ...
;             G_WAIT_V(6); G_BAR; G_MMA(1, 1, At, B1); G_BAR;
;             G_LDB(B0, 1, 0); G_SCHED; G_LDA(At, 1, 0); G_STAGE(G_SA(0, 1), a2 + hstep);
;             G_WAIT_L(8); G_BAR; G_WAIT_L(0); G_MMA(0, 0, At, B0); G_BAR; G_SCHED;
;             G_LDB(B1, 1, 1); G_STAGE(G_SB(1, 0), b3);
;             G_BAR; G_WAIT_L(0); G_MMA(0, 1, At, B1); G_BAR;
;             G_LDA(At, 1, 1); G_STAGE(G_SA(1, 0), a3);
;             G_BAR; G_WAIT_L(0); G_MMA(1, 0, At, B0); G_BAR; G_SCHED;
;             G_STAGE(G_SB(1, 1), b3 + hstep);
	v_mfma_f32_16x16x32_bf16 v[68:71], v[230:233], v[140:143], v[68:71]
	v_mfma_f32_16x16x32_bf16 v[64:67], v[238:241], v[140:143], v[64:67]
	v_mfma_f32_16x16x32_bf16 v[52:55], v[230:233], v[152:155], v[52:55]
	v_mfma_f32_16x16x32_bf16 v[48:51], v[238:241], v[152:155], v[48:51]
	v_mfma_f32_16x16x32_bf16 v[36:39], v[230:233], v[188:191], v[36:39]
	v_mfma_f32_16x16x32_bf16 v[32:35], v[238:241], v[188:191], v[32:35]
	v_mfma_f32_16x16x32_bf16 v[20:23], v[230:233], v[222:225], v[20:23]
	v_mfma_f32_16x16x32_bf16 v[16:19], v[238:241], v[222:225], v[16:19]
	v_mfma_f32_16x16x32_bf16 v[68:71], v[234:237], v[148:151], v[68:71]
	v_mfma_f32_16x16x32_bf16 v[64:67], v[242:245], v[148:151], v[64:67]
	v_mfma_f32_16x16x32_bf16 v[52:55], v[234:237], v[156:159], v[52:55]
	v_mfma_f32_16x16x32_bf16 v[48:51], v[242:245], v[156:159], v[48:51]
	v_mfma_f32_16x16x32_bf16 v[36:39], v[234:237], v[192:195], v[36:39]
	v_mfma_f32_16x16x32_bf16 v[32:35], v[242:245], v[192:195], v[32:35]
	v_mfma_f32_16x16x32_bf16 v[20:23], v[234:237], v[226:229], v[20:23]
	v_mfma_f32_16x16x32_bf16 v[16:19], v[242:245], v[226:229], v[16:19]
	s_barrier
	ds_read_b128 v[124:127], v217 offset:32768
	ds_read_b128 v[128:131], v217 offset:33792
	ds_read_b128 v[132:135], v217 offset:34816
	ds_read_b128 v[136:139], v217 offset:35840
	s_mov_b32 m0, s60
	ds_read_b128 v[140:143], v186 offset:32768
	ds_read_b128 v[148:151], v186 offset:33792
	ds_read_b128 v[152:155], v186 offset:34816
	ds_read_b128 v[156:159], v186 offset:35840
	ds_read_b128 v[188:191], v186 offset:36864
	ds_read_b128 v[192:195], v186 offset:37888
	ds_read_b128 v[222:225], v186 offset:38912
	global_load_lds_dwordx4 v0, s[54:55]
	s_mov_b32 m0, s61
	ds_read_b128 v[226:229], v186 offset:39936
	global_load_lds_dwordx4 v2, s[54:55]
	s_waitcnt lgkmcnt(8)
	s_barrier
	s_waitcnt lgkmcnt(0)
	s_waitcnt lgkmcnt(0)
	v_mfma_f32_16x16x32_bf16 v[164:167], v[124:127], v[140:143], v[164:167]
	v_mfma_f32_16x16x32_bf16 v[160:163], v[132:135], v[140:143], v[160:163]
	v_mfma_f32_16x16x32_bf16 v[116:119], v[124:127], v[152:155], v[116:119]
	v_mfma_f32_16x16x32_bf16 v[112:115], v[132:135], v[152:155], v[112:115]
	v_mfma_f32_16x16x32_bf16 v[100:103], v[124:127], v[188:191], v[100:103]
	v_mfma_f32_16x16x32_bf16 v[96:99], v[132:135], v[188:191], v[96:99]
	v_mfma_f32_16x16x32_bf16 v[84:87], v[124:127], v[222:225], v[84:87]
	v_mfma_f32_16x16x32_bf16 v[80:83], v[132:135], v[222:225], v[80:83]
	v_mfma_f32_16x16x32_bf16 v[164:167], v[128:131], v[148:151], v[164:167]
	v_mfma_f32_16x16x32_bf16 v[160:163], v[136:139], v[148:151], v[160:163]
	v_mfma_f32_16x16x32_bf16 v[116:119], v[128:131], v[156:159], v[116:119]
	v_mfma_f32_16x16x32_bf16 v[112:115], v[136:139], v[156:159], v[112:115]
	v_mfma_f32_16x16x32_bf16 v[100:103], v[128:131], v[192:195], v[100:103]
	v_mfma_f32_16x16x32_bf16 v[96:99], v[136:139], v[192:195], v[96:99]
	v_mfma_f32_16x16x32_bf16 v[84:87], v[128:131], v[226:229], v[84:87]
	v_mfma_f32_16x16x32_bf16 v[80:83], v[136:139], v[226:229], v[80:83]
	s_barrier
	s_add_i32 m0, s57, 0x18000
	ds_read_b128 v[230:233], v217 offset:49152
	ds_read_b128 v[234:237], v217 offset:50176
	ds_read_b128 v[238:241], v217 offset:51200
	s_add_u32 s98, s52, 0x80
	s_addc_u32 s99, s53, 0
	global_load_lds_dwordx4 v0, s[98:99]
	s_add_i32 m0, s57, 0x1a000
	ds_read_b128 v[242:245], v217 offset:52224
	global_load_lds_dwordx4 v2, s[98:99]
	s_barrier
	s_waitcnt lgkmcnt(0)
	s_waitcnt lgkmcnt(0)
	v_mfma_f32_16x16x32_bf16 v[144:147], v[230:233], v[140:143], v[144:147]
	v_mfma_f32_16x16x32_bf16 v[120:123], v[238:241], v[140:143], v[120:123]
	v_mfma_f32_16x16x32_bf16 v[108:111], v[230:233], v[152:155], v[108:111]
	v_mfma_f32_16x16x32_bf16 v[104:107], v[238:241], v[152:155], v[104:107]
	v_mfma_f32_16x16x32_bf16 v[92:95], v[230:233], v[188:191], v[92:95]
	v_mfma_f32_16x16x32_bf16 v[88:91], v[238:241], v[188:191], v[88:91]
	v_mfma_f32_16x16x32_bf16 v[76:79], v[230:233], v[222:225], v[76:79]
	v_mfma_f32_16x16x32_bf16 v[72:75], v[238:241], v[222:225], v[72:75]
	v_mfma_f32_16x16x32_bf16 v[144:147], v[234:237], v[148:151], v[144:147]
	v_mfma_f32_16x16x32_bf16 v[120:123], v[242:245], v[148:151], v[120:123]
	v_mfma_f32_16x16x32_bf16 v[108:111], v[234:237], v[156:159], v[108:111]
	v_mfma_f32_16x16x32_bf16 v[104:107], v[242:245], v[156:159], v[104:107]
	v_mfma_f32_16x16x32_bf16 v[92:95], v[234:237], v[192:195], v[92:95]
	v_mfma_f32_16x16x32_bf16 v[88:91], v[242:245], v[192:195], v[88:91]
	v_mfma_f32_16x16x32_bf16 v[76:79], v[234:237], v[226:229], v[76:79]
	v_mfma_f32_16x16x32_bf16 v[72:75], v[242:245], v[226:229], v[72:75]
	s_mov_b32 m0, s62
	s_barrier
	ds_read_b128 v[140:143], v186 offset:49152
	ds_read_b128 v[148:151], v186 offset:50176
	ds_read_b128 v[152:155], v186 offset:51200
	ds_read_b128 v[156:159], v186 offset:52224
	ds_read_b128 v[188:191], v186 offset:53248
	ds_read_b128 v[192:195], v186 offset:54272
	ds_read_b128 v[222:225], v186 offset:55296
	s_add_u32 s98, s54, 0xfffc0080
	s_addc_u32 s99, s55, -1
	global_load_lds_dwordx4 v0, s[98:99]
	s_mov_b32 m0, s63
	ds_read_b128 v[226:229], v186 offset:56320
	global_load_lds_dwordx4 v2, s[98:99]
	s_barrier
	s_waitcnt lgkmcnt(0)
	s_waitcnt lgkmcnt(0)
	v_mfma_f32_16x16x32_bf16 v[60:63], v[124:127], v[140:143], v[60:63]
	v_mfma_f32_16x16x32_bf16 v[56:59], v[132:135], v[140:143], v[56:59]
	v_mfma_f32_16x16x32_bf16 v[44:47], v[124:127], v[152:155], v[44:47]
	v_mfma_f32_16x16x32_bf16 v[40:43], v[132:135], v[152:155], v[40:43]
	v_mfma_f32_16x16x32_bf16 v[28:31], v[124:127], v[188:191], v[28:31]
	v_mfma_f32_16x16x32_bf16 v[24:27], v[132:135], v[188:191], v[24:27]
	v_mfma_f32_16x16x32_bf16 v[12:15], v[124:127], v[222:225], v[12:15]
	v_mfma_f32_16x16x32_bf16 v[8:11], v[132:135], v[222:225], v[8:11]
	v_mfma_f32_16x16x32_bf16 v[60:63], v[128:131], v[148:151], v[60:63]
	v_mfma_f32_16x16x32_bf16 v[56:59], v[136:139], v[148:151], v[56:59]
	v_mfma_f32_16x16x32_bf16 v[44:47], v[128:131], v[156:159], v[44:47]
	v_mfma_f32_16x16x32_bf16 v[40:43], v[136:139], v[156:159], v[40:43]
	v_mfma_f32_16x16x32_bf16 v[28:31], v[128:131], v[192:195], v[28:31]
	v_mfma_f32_16x16x32_bf16 v[24:27], v[136:139], v[192:195], v[24:27]
	v_mfma_f32_16x16x32_bf16 v[12:15], v[128:131], v[226:229], v[12:15]
	v_mfma_f32_16x16x32_bf16 v[8:11], v[136:139], v[226:229], v[8:11]
	s_barrier
	s_add_i32 m0, s57, 0x1c000
	s_add_u32 s52, s52, 0x40080
	s_addc_u32 s53, s53, 0
	global_load_lds_dwordx4 v0, s[52:53]
	s_add_i32 m0, s57, 0x1e000
	s_add_i32 s73, s73, 2
	global_load_lds_dwordx4 v2, s[52:53]
	s_add_u32 s71, s71, 0x100
	s_addc_u32 s72, s72, 0
	s_add_u32 s50, s50, 0x100
	s_addc_u32 s51, s51, 0
	s_cmp_gt_u32 s73, 13
	s_cbranch_scc1 .LrotX_78
	s_cmp_lg_u32 s73, 12
	s_cselect_b64 s[52:53], -1, 0
	s_add_u32 s12, s50, 0xfffc0080
	s_addc_u32 s26, s51, -1
	s_and_b64 s[52:53], s[52:53], exec
	s_cselect_b32 s55, s26, s43
	s_cselect_b32 s54, s12, s42
	s_cselect_b32 s53, s72, s15
	s_cselect_b32 s52, s71, s69

; #define G_STAGE(bufoff, gbase) do { _Pragma("unroll") for (int _i = 0; _i < 2; ++_i) \
;         __builtin_amdgcn_global_load_lds((const unsigned*)((const char*)(gbase) + voff[_i]), (LAS unsigned*)(lds + (bufoff) + ldsw + _i * 8192), 16, 0, 0); } while (0)
; #define G_LDA(dst, b, h) do { _Pragma("unroll") for (int m = 0; m < 4; ++m) _Pragma("unroll") for (int k = 0; k < 2; ++k) dst[m][k] = *(const LAS bf16x8*)(lds + G_SA(b, h) + aoff + m * 2048 + k * 1024); } while (0)
; #define G_LDB(dst, b, h) do { _Pragma("unroll") for (int n = 0; n < 2; ++n) _Pragma("unroll") for (int k = 0; k < 2; ++k) dst[n][k] = *(const LAS bf16x8*)(lds + G_SB(b, h) + boff + n * 2048 + k * 1024); } while (0)
; #define G_MMA(ai, bj, At, Bt) do { __builtin_amdgcn_s_setprio(1); _Pragma("unroll") for (int m = 0; m < 4; ++m) _Pragma("unroll") for (int n = 0; n < 2; ++n) _Pragma("unroll") for (int k = 0; k < 2; ++k) \
;         acc[ai][bj][m][n] = MFMA16(Bt[n][k], At[m][k], acc[ai][bj][m][n]); __builtin_amdgcn_s_setprio(0); } while (0)
; #define G_WAIT_V(n) asm volatile("s_waitcnt vmcnt(" #n ")" ::: "memory")
; #define G_WAIT_L(n) asm volatile("s_waitcnt lgkmcnt(" #n ")" ::: "memory")
; #define G_BAR __builtin_amdgcn_s_barrier()
; #define G_SCHED __builtin_amdgcn_sched_barrier(0)
; template <class Epi>
; __device__ __forceinline__ void gemm_phase(LAS unsigned char* lds, const bf16_t* Ag, const bf16_t* Btg, const int K, const int nM, const int nN, const Epi& E) {
;     ...
;             G_LDB(B0, 0, 0); G_SCHED; G_LDA(At, 0, 0); G_STAGE(G_SA(1, 1), a1 + hstep);
;             G_WAIT_L(8); G_BAR; G_WAIT_L(0); G_MMA(0, 0, At, B0); G_BAR; G_SCHED;
;             G_LDB(B1, 0, 1); G_STAGE(G_SB(0, 0), b2);
;             G_BAR; G_WAIT_L(0); G_MMA(0, 1, At, B1); G_BAR;
;             G_LDA(At, 0, 1); G_STAGE(G_SA(0, 0), a2);
;             G_BAR; G_WAIT_L(0); G_MMA(1, 0, At, B0); G_BAR; G_SCHED;
;             G_STAGE(G_SB(0, 1), b2 + hstep);
;             G_WAIT_V(6); G_BAR; G_MMA(1, 1, At, B1); G_BAR;
.LmainW_153:
	ds_read_b128 v[144:147], v217
	ds_read_b128 v[148:151], v217 offset:1024
	ds_read_b128 v[152:155], v217 offset:2048
	ds_read_b128 v[156:159], v217 offset:3072
	s_add_i32 m0, s72, 0xc000
	ds_read_b128 v[160:163], v230
	ds_read_b128 v[164:167], v230 offset:1024
	ds_read_b128 v[168:171], v230 offset:2048
	ds_read_b128 v[172:175], v230 offset:3072
	ds_read_b128 v[180:183], v230 offset:4096
	ds_read_b128 v[184:187], v230 offset:5120
	ds_read_b128 v[188:191], v230 offset:6144
	global_load_lds_dwordx4 v138, s[64:65]
	s_add_i32 m0, s72, 0xe000
	ds_read_b128 v[192:195], v230 offset:7168
	global_load_lds_dwordx4 v136, s[64:65]
	s_waitcnt lgkmcnt(8)
	s_barrier
	s_waitcnt lgkmcnt(0)
	s_waitcnt lgkmcnt(0)
	v_mfma_f32_16x16x32_bf16 v[132:135], v[144:147], v[160:163], v[132:135]
	v_mfma_f32_16x16x32_bf16 v[128:131], v[152:155], v[160:163], v[128:131]
	v_mfma_f32_16x16x32_bf16 v[116:119], v[144:147], v[168:171], v[116:119]
	v_mfma_f32_16x16x32_bf16 v[112:115], v[152:155], v[168:171], v[112:115]
	v_mfma_f32_16x16x32_bf16 v[100:103], v[144:147], v[180:183], v[100:103]
	v_mfma_f32_16x16x32_bf16 v[96:99], v[152:155], v[180:183], v[96:99]
	v_mfma_f32_16x16x32_bf16 v[84:87], v[144:147], v[188:191], v[84:87]
	v_mfma_f32_16x16x32_bf16 v[80:83], v[152:155], v[188:191], v[80:83]
	v_mfma_f32_16x16x32_bf16 v[132:135], v[148:151], v[164:167], v[132:135]
	v_mfma_f32_16x16x32_bf16 v[128:131], v[156:159], v[164:167], v[128:131]
	v_mfma_f32_16x16x32_bf16 v[116:119], v[148:151], v[172:175], v[116:119]
	v_mfma_f32_16x16x32_bf16 v[112:115], v[156:159], v[172:175], v[112:115]
	v_mfma_f32_16x16x32_bf16 v[100:103], v[148:151], v[184:187], v[100:103]
	v_mfma_f32_16x16x32_bf16 v[96:99], v[156:159], v[184:187], v[96:99]
	v_mfma_f32_16x16x32_bf16 v[84:87], v[148:151], v[192:195], v[84:87]
	v_mfma_f32_16x16x32_bf16 v[80:83], v[156:159], v[192:195], v[80:83]
	s_barrier
	s_add_i32 m0, s21, 0x10000
	ds_read_b128 v[232:235], v217 offset:16384
	ds_read_b128 v[236:239], v217 offset:17408
	ds_read_b128 v[240:243], v217 offset:18432
	global_load_lds_dwordx4 v0, s[68:69]
	s_add_i32 m0, s21, 0x12000
	ds_read_b128 v[244:247], v217 offset:19456
	global_load_lds_dwordx4 v2, s[68:69]
	s_barrier
	s_waitcnt lgkmcnt(0)
	s_waitcnt lgkmcnt(0)
	v_mfma_f32_16x16x32_bf16 v[124:127], v[232:235], v[160:163], v[124:127]
	v_mfma_f32_16x16x32_bf16 v[120:123], v[240:243], v[160:163], v[120:123]
	v_mfma_f32_16x16x32_bf16 v[108:111], v[232:235], v[168:171], v[108:111]
	v_mfma_f32_16x16x32_bf16 v[104:107], v[240:243], v[168:171], v[104:107]
	v_mfma_f32_16x16x32_bf16 v[92:95], v[232:235], v[180:183], v[92:95]
	v_mfma_f32_16x16x32_bf16 v[88:91], v[240:243], v[180:183], v[88:91]
	v_mfma_f32_16x16x32_bf16 v[76:79], v[232:235], v[188:191], v[76:79]
	v_mfma_f32_16x16x32_bf16 v[72:75], v[240:243], v[188:191], v[72:75]
	v_mfma_f32_16x16x32_bf16 v[124:127], v[236:239], v[164:167], v[124:127]
	v_mfma_f32_16x16x32_bf16 v[120:123], v[244:247], v[164:167], v[120:123]
	v_mfma_f32_16x16x32_bf16 v[108:111], v[236:239], v[172:175], v[108:111]
	v_mfma_f32_16x16x32_bf16 v[104:107], v[244:247], v[172:175], v[104:107]
	v_mfma_f32_16x16x32_bf16 v[92:95], v[236:239], v[184:187], v[92:95]
	v_mfma_f32_16x16x32_bf16 v[88:91], v[244:247], v[184:187], v[88:91]
	v_mfma_f32_16x16x32_bf16 v[76:79], v[236:239], v[192:195], v[76:79]
	v_mfma_f32_16x16x32_bf16 v[72:75], v[244:247], v[192:195], v[72:75]
	s_mov_b32 m0, s72
	s_barrier
	ds_read_b128 v[160:163], v230 offset:16384
	ds_read_b128 v[164:167], v230 offset:17408
	ds_read_b128 v[168:171], v230 offset:18432
	ds_read_b128 v[172:175], v230 offset:19456
	ds_read_b128 v[180:183], v230 offset:20480
	ds_read_b128 v[184:187], v230 offset:21504
	ds_read_b128 v[188:191], v230 offset:22528
	global_load_lds_dwordx4 v0, s[70:71]
	s_mov_b32 m0, s73
	ds_read_b128 v[192:195], v230 offset:23552
	global_load_lds_dwordx4 v2, s[70:71]
	s_barrier
	s_waitcnt lgkmcnt(0)
	s_waitcnt lgkmcnt(0)
	v_mfma_f32_16x16x32_bf16 v[68:71], v[144:147], v[160:163], v[68:71]
	v_mfma_f32_16x16x32_bf16 v[64:67], v[152:155], v[160:163], v[64:67]
	v_mfma_f32_16x16x32_bf16 v[52:55], v[144:147], v[168:171], v[52:55]
	v_mfma_f32_16x16x32_bf16 v[48:51], v[152:155], v[168:171], v[48:51]
	v_mfma_f32_16x16x32_bf16 v[36:39], v[144:147], v[180:183], v[36:39]
	v_mfma_f32_16x16x32_bf16 v[32:35], v[152:155], v[180:183], v[32:35]
	v_mfma_f32_16x16x32_bf16 v[20:23], v[144:147], v[188:191], v[20:23]
	v_mfma_f32_16x16x32_bf16 v[16:19], v[152:155], v[188:191], v[16:19]
	v_mfma_f32_16x16x32_bf16 v[68:71], v[148:151], v[164:167], v[68:71]
	v_mfma_f32_16x16x32_bf16 v[64:67], v[156:159], v[164:167], v[64:67]
	v_mfma_f32_16x16x32_bf16 v[52:55], v[148:151], v[172:175], v[52:55]
	v_mfma_f32_16x16x32_bf16 v[48:51], v[156:159], v[172:175], v[48:51]
	v_mfma_f32_16x16x32_bf16 v[36:39], v[148:151], v[184:187], v[36:39]
	v_mfma_f32_16x16x32_bf16 v[32:35], v[156:159], v[184:187], v[32:35]
	v_mfma_f32_16x16x32_bf16 v[20:23], v[148:151], v[192:195], v[20:23]
	v_mfma_f32_16x16x32_bf16 v[16:19], v[156:159], v[192:195], v[16:19]
	s_barrier
	s_add_i32 m0, s21, 0x14000
	s_add_u32 s64, s68, 0x40000
	s_addc_u32 s65, s69, 0
	global_load_lds_dwordx4 v0, s[64:65]
	s_add_i32 m0, s21, 0x16000
	s_add_u32 s98, s70, 0x40000
	s_addc_u32 s99, s71, 0
	global_load_lds_dwordx4 v2, s[64:65]
	s_waitcnt vmcnt(6)
	s_barrier
; #define G_STAGE(bufoff, gbase) do { _Pragma("unroll") for (int _i = 0; _i < 2; ++_i) \
;         __builtin_amdgcn_global_load_lds((const unsigned*)((const char*)(gbase) + voff[_i]), (LAS unsigned*)(lds + (bufoff) + ldsw + _i * 8192), 16, 0, 0); } while (0)
; #define G_LDA(dst, b, h) do { _Pragma("unroll") for (int m = 0; m < 4; ++m) _Pragma("unroll") for (int k = 0; k < 2; ++k) dst[m][k] = *(const LAS bf16x8*)(lds + G_SA(b, h) + aoff + m * 2048 + k * 1024); } while (0)
; #define G_LDB(dst, b, h) do { _Pragma("unroll") for (int n = 0; n < 2; ++n) _Pragma("unroll") for (int k = 0; k < 2; ++k) dst[n][k] = *(const LAS bf16x8*)(lds + G_SB(b, h) + boff + n * 2048 + k * 1024); } while (0)
; #define G_MMA(ai, bj, At, Bt) do { __builtin_amdgcn_s_setprio(1); _Pragma("unroll") for (int m = 0; m < 4; ++m) _Pragma("unroll") for (int n = 0; n < 2; ++n) _Pragma("unroll") for (int k = 0; k < 2; ++k) \
;         acc[ai][bj][m][n] = MFMA16(Bt[n][k], At[m][k], acc[ai][bj][m][n]); __builtin_amdgcn_s_setprio(0); } while (0)
; #define G_WAIT_V(n) asm volatile("s_waitcnt vmcnt(" #n ")" ::: "memory")
; #define G_WAIT_L(n) asm volatile("s_waitcnt lgkmcnt(" #n ")" ::: "memory")
; #define G_BAR __builtin_amdgcn_s_barrier()
; #define G_SCHED __builtin_amdgcn_sched_barrier(0)
; template <class Epi>
; __device__ __forceinline__ void gemm_phase(LAS unsigned char* lds, const bf16_t* Ag, const bf16_t* Btg, const int K, const int nM, const int nN, const Epi& E) {
;     ...
;         for (int t = 0; t < nt; t += 2) {
;             const bool last = (t == nt - 2);
;             const char* a1 = cA + (size_t)(t + 1) * kstep;
;             const char* a2 = last ? nA : cA + (size_t)(t + 2) * kstep; const char* b2 = last ? nB : cB + (size_t)(t + 2) * kstep;
;             const char* a3 = a2 + kstep; const char* b3 = b2 + kstep;
;     ...
;             G_WAIT_V(6); G_BAR; G_MMA(1, 1, At, B1); G_BAR;
;             G_LDB(B0, 1, 0); G_SCHED; G_LDA(At, 1, 0); G_STAGE(G_SA(0, 1), a2 + hstep);
;             G_WAIT_L(8); G_BAR; G_WAIT_L(0); G_MMA(0, 0, At, B0); G_BAR; G_SCHED;
;             G_LDB(B1, 1, 1); G_STAGE(G_SB(1, 0), b3);
;             G_BAR; G_WAIT_L(0); G_MMA(0, 1, At, B1); G_BAR;
;             G_LDA(At, 1, 1); G_STAGE(G_SA(1, 0), a3);
;             G_BAR; G_WAIT_L(0); G_MMA(1, 0, At, B0); G_BAR; G_SCHED;
;             G_STAGE(G_SB(1, 1), b3 + hstep);
	v_mfma_f32_16x16x32_bf16 v[60:63], v[232:235], v[160:163], v[60:63]
	v_mfma_f32_16x16x32_bf16 v[56:59], v[240:243], v[160:163], v[56:59]
	v_mfma_f32_16x16x32_bf16 v[44:47], v[232:235], v[168:171], v[44:47]
	v_mfma_f32_16x16x32_bf16 v[40:43], v[240:243], v[168:171], v[40:43]
	v_mfma_f32_16x16x32_bf16 v[28:31], v[232:235], v[180:183], v[28:31]
	v_mfma_f32_16x16x32_bf16 v[24:27], v[240:243], v[180:183], v[24:27]
	v_mfma_f32_16x16x32_bf16 v[12:15], v[232:235], v[188:191], v[12:15]
	v_mfma_f32_16x16x32_bf16 v[8:11], v[240:243], v[188:191], v[8:11]
	v_mfma_f32_16x16x32_bf16 v[60:63], v[236:239], v[164:167], v[60:63]
	v_mfma_f32_16x16x32_bf16 v[56:59], v[244:247], v[164:167], v[56:59]
	v_mfma_f32_16x16x32_bf16 v[44:47], v[236:239], v[172:175], v[44:47]
	v_mfma_f32_16x16x32_bf16 v[40:43], v[244:247], v[172:175], v[40:43]
	v_mfma_f32_16x16x32_bf16 v[28:31], v[236:239], v[184:187], v[28:31]
	v_mfma_f32_16x16x32_bf16 v[24:27], v[244:247], v[184:187], v[24:27]
	v_mfma_f32_16x16x32_bf16 v[12:15], v[236:239], v[192:195], v[12:15]
	v_mfma_f32_16x16x32_bf16 v[8:11], v[244:247], v[192:195], v[8:11]
	s_barrier
	ds_read_b128 v[144:147], v217 offset:32768
	ds_read_b128 v[148:151], v217 offset:33792
	ds_read_b128 v[152:155], v217 offset:34816
	ds_read_b128 v[156:159], v217 offset:35840
	s_mov_b32 m0, s74
	ds_read_b128 v[160:163], v230 offset:32768
	ds_read_b128 v[164:167], v230 offset:33792
	ds_read_b128 v[168:171], v230 offset:34816
	ds_read_b128 v[172:175], v230 offset:35840
	ds_read_b128 v[180:183], v230 offset:36864
	ds_read_b128 v[184:187], v230 offset:37888
	ds_read_b128 v[188:191], v230 offset:38912
	global_load_lds_dwordx4 v0, s[98:99]
	s_mov_b32 m0, s75
	ds_read_b128 v[192:195], v230 offset:39936
	global_load_lds_dwordx4 v2, s[98:99]
	s_waitcnt lgkmcnt(8)
	s_barrier
	s_waitcnt lgkmcnt(0)
	s_waitcnt lgkmcnt(0)
	v_mfma_f32_16x16x32_bf16 v[132:135], v[144:147], v[160:163], v[132:135]
	v_mfma_f32_16x16x32_bf16 v[128:131], v[152:155], v[160:163], v[128:131]
	v_mfma_f32_16x16x32_bf16 v[116:119], v[144:147], v[168:171], v[116:119]
	v_mfma_f32_16x16x32_bf16 v[112:115], v[152:155], v[168:171], v[112:115]
	v_mfma_f32_16x16x32_bf16 v[100:103], v[144:147], v[180:183], v[100:103]
	v_mfma_f32_16x16x32_bf16 v[96:99], v[152:155], v[180:183], v[96:99]
	v_mfma_f32_16x16x32_bf16 v[84:87], v[144:147], v[188:191], v[84:87]
	v_mfma_f32_16x16x32_bf16 v[80:83], v[152:155], v[188:191], v[80:83]
	v_mfma_f32_16x16x32_bf16 v[132:135], v[148:151], v[164:167], v[132:135]
	v_mfma_f32_16x16x32_bf16 v[128:131], v[156:159], v[164:167], v[128:131]
	v_mfma_f32_16x16x32_bf16 v[116:119], v[148:151], v[172:175], v[116:119]
	v_mfma_f32_16x16x32_bf16 v[112:115], v[156:159], v[172:175], v[112:115]
	v_mfma_f32_16x16x32_bf16 v[100:103], v[148:151], v[184:187], v[100:103]
	v_mfma_f32_16x16x32_bf16 v[96:99], v[156:159], v[184:187], v[96:99]
	v_mfma_f32_16x16x32_bf16 v[84:87], v[148:151], v[192:195], v[84:87]
	v_mfma_f32_16x16x32_bf16 v[80:83], v[156:159], v[192:195], v[80:83]
	s_barrier
	s_add_i32 m0, s21, 0x18000
	ds_read_b128 v[232:235], v217 offset:49152
	ds_read_b128 v[236:239], v217 offset:50176
	ds_read_b128 v[240:243], v217 offset:51200
	s_add_u32 s98, s68, 0x80
	s_addc_u32 s99, s69, 0
	global_load_lds_dwordx4 v0, s[98:99]
	s_add_i32 m0, s21, 0x1a000
	ds_read_b128 v[244:247], v217 offset:52224
	global_load_lds_dwordx4 v2, s[98:99]
	s_barrier
	s_waitcnt lgkmcnt(0)
	s_waitcnt lgkmcnt(0)
	v_mfma_f32_16x16x32_bf16 v[124:127], v[232:235], v[160:163], v[124:127]
	v_mfma_f32_16x16x32_bf16 v[120:123], v[240:243], v[160:163], v[120:123]
	v_mfma_f32_16x16x32_bf16 v[108:111], v[232:235], v[168:171], v[108:111]
	v_mfma_f32_16x16x32_bf16 v[104:107], v[240:243], v[168:171], v[104:107]
	v_mfma_f32_16x16x32_bf16 v[92:95], v[232:235], v[180:183], v[92:95]
	v_mfma_f32_16x16x32_bf16 v[88:91], v[240:243], v[180:183], v[88:91]
	v_mfma_f32_16x16x32_bf16 v[76:79], v[232:235], v[188:191], v[76:79]
	v_mfma_f32_16x16x32_bf16 v[72:75], v[240:243], v[188:191], v[72:75]
	v_mfma_f32_16x16x32_bf16 v[124:127], v[236:239], v[164:167], v[124:127]
	v_mfma_f32_16x16x32_bf16 v[120:123], v[244:247], v[164:167], v[120:123]
	v_mfma_f32_16x16x32_bf16 v[108:111], v[236:239], v[172:175], v[108:111]
	v_mfma_f32_16x16x32_bf16 v[104:107], v[244:247], v[172:175], v[104:107]
	v_mfma_f32_16x16x32_bf16 v[92:95], v[236:239], v[184:187], v[92:95]
	v_mfma_f32_16x16x32_bf16 v[88:91], v[244:247], v[184:187], v[88:91]
	v_mfma_f32_16x16x32_bf16 v[76:79], v[236:239], v[192:195], v[76:79]
	v_mfma_f32_16x16x32_bf16 v[72:75], v[244:247], v[192:195], v[72:75]
	s_mov_b32 m0, s76
	s_barrier
	ds_read_b128 v[160:163], v230 offset:49152
	ds_read_b128 v[164:167], v230 offset:50176
	ds_read_b128 v[168:171], v230 offset:51200
	ds_read_b128 v[172:175], v230 offset:52224
	ds_read_b128 v[180:183], v230 offset:53248
	ds_read_b128 v[184:187], v230 offset:54272
	ds_read_b128 v[188:191], v230 offset:55296
	s_add_u32 s98, s70, 0x80
	s_addc_u32 s99, s71, 0
	global_load_lds_dwordx4 v0, s[98:99]
	s_mov_b32 m0, s77
	ds_read_b128 v[192:195], v230 offset:56320
	global_load_lds_dwordx4 v2, s[98:99]
	s_barrier
	s_waitcnt lgkmcnt(0)
	s_waitcnt lgkmcnt(0)
	v_mfma_f32_16x16x32_bf16 v[68:71], v[144:147], v[160:163], v[68:71]
	v_mfma_f32_16x16x32_bf16 v[64:67], v[152:155], v[160:163], v[64:67]
	v_mfma_f32_16x16x32_bf16 v[52:55], v[144:147], v[168:171], v[52:55]
	v_mfma_f32_16x16x32_bf16 v[48:51], v[152:155], v[168:171], v[48:51]
	v_mfma_f32_16x16x32_bf16 v[36:39], v[144:147], v[180:183], v[36:39]
	v_mfma_f32_16x16x32_bf16 v[32:35], v[152:155], v[180:183], v[32:35]
	v_mfma_f32_16x16x32_bf16 v[20:23], v[144:147], v[188:191], v[20:23]
	v_mfma_f32_16x16x32_bf16 v[16:19], v[152:155], v[188:191], v[16:19]
	v_mfma_f32_16x16x32_bf16 v[68:71], v[148:151], v[164:167], v[68:71]
	v_mfma_f32_16x16x32_bf16 v[64:67], v[156:159], v[164:167], v[64:67]
	v_mfma_f32_16x16x32_bf16 v[52:55], v[148:151], v[172:175], v[52:55]
	v_mfma_f32_16x16x32_bf16 v[48:51], v[156:159], v[172:175], v[48:51]
	v_mfma_f32_16x16x32_bf16 v[36:39], v[148:151], v[184:187], v[36:39]
	v_mfma_f32_16x16x32_bf16 v[32:35], v[156:159], v[184:187], v[32:35]
	v_mfma_f32_16x16x32_bf16 v[20:23], v[148:151], v[192:195], v[20:23]
	v_mfma_f32_16x16x32_bf16 v[16:19], v[156:159], v[192:195], v[16:19]
	s_barrier
	s_add_i32 m0, s21, 0x1c000
	s_add_u32 s64, s68, 0x40080
	s_addc_u32 s65, s69, 0
	global_load_lds_dwordx4 v0, s[64:65]
	s_add_i32 m0, s21, 0x1e000
	s_add_i32 s42, s42, 2
	global_load_lds_dwordx4 v2, s[64:65]
	s_add_u32 s57, s57, 0x100
	s_addc_u32 s61, s61, 0
	s_mov_b64 s[64:65], s[66:67]
	s_cmp_gt_u32 s42, 13
	s_cbranch_scc1 .LrotX_153
	s_cmp_lg_u32 s42, 12
	s_cselect_b64 s[68:69], -1, 0
	s_add_u32 s66, s64, 0x100
	s_addc_u32 s67, s65, 0
	s_and_b64 s[68:69], s[68:69], exec
	s_cselect_b32 s71, s67, s55
	s_cselect_b32 s70, s66, s54
	s_cselect_b32 s69, s61, s14
	s_cselect_b32 s68, s57, s15

; #define G_STAGE(bufoff, gbase) do { _Pragma("unroll") for (int _i = 0; _i < 2; ++_i) \
;         __builtin_amdgcn_global_load_lds((const unsigned*)((const char*)(gbase) + voff[_i]), (LAS unsigned*)(lds + (bufoff) + ldsw + _i * 8192), 16, 0, 0); } while (0)
; #define G_LDA(dst, b, h) do { _Pragma("unroll") for (int m = 0; m < 4; ++m) _Pragma("unroll") for (int k = 0; k < 2; ++k) dst[m][k] = *(const LAS bf16x8*)(lds + G_SA(b, h) + aoff + m * 2048 + k * 1024); } while (0)
; #define G_LDB(dst, b, h) do { _Pragma("unroll") for (int n = 0; n < 2; ++n) _Pragma("unroll") for (int k = 0; k < 2; ++k) dst[n][k] = *(const LAS bf16x8*)(lds + G_SB(b, h) + boff + n * 2048 + k * 1024); } while (0)
; #define G_MMA(ai, bj, At, Bt) do { __builtin_amdgcn_s_setprio(1); _Pragma("unroll") for (int m = 0; m < 4; ++m) _Pragma("unroll") for (int n = 0; n < 2; ++n) _Pragma("unroll") for (int k = 0; k < 2; ++k) \
;         acc[ai][bj][m][n] = MFMA16(Bt[n][k], At[m][k], acc[ai][bj][m][n]); __builtin_amdgcn_s_setprio(0); } while (0)
; #define G_WAIT_V(n) asm volatile("s_waitcnt vmcnt(" #n ")" ::: "memory")
; #define G_WAIT_L(n) asm volatile("s_waitcnt lgkmcnt(" #n ")" ::: "memory")
; #define G_BAR __builtin_amdgcn_s_barrier()
; #define G_SCHED __builtin_amdgcn_sched_barrier(0)
; template <class Epi>
; __device__ __forceinline__ void gemm_phase(LAS unsigned char* lds, const bf16_t* Ag, const bf16_t* Btg, const int K, const int nM, const int nN, const Epi& E) {
;     ...
;             G_LDB(B0, 0, 0); G_SCHED; G_LDA(At, 0, 0); G_STAGE(G_SA(1, 1), a1 + hstep);
;             G_WAIT_L(8); G_BAR; G_WAIT_L(0); G_MMA(0, 0, At, B0); G_BAR; G_SCHED;
;             G_LDB(B1, 0, 1); G_STAGE(G_SB(0, 0), b2);
;             G_BAR; G_WAIT_L(0); G_MMA(0, 1, At, B1); G_BAR;
;             G_LDA(At, 0, 1); G_STAGE(G_SA(0, 0), a2);
;             G_BAR; G_WAIT_L(0); G_MMA(1, 0, At, B0); G_BAR; G_SCHED;
;             G_STAGE(G_SB(0, 1), b2 + hstep);
;             G_WAIT_V(6); G_BAR; G_MMA(1, 1, At, B1); G_BAR;
.LmainW_744:
	ds_read_b128 v[140:143], v217
	ds_read_b128 v[144:147], v217 offset:1024
	ds_read_b128 v[148:151], v217 offset:2048
	ds_read_b128 v[152:155], v217 offset:3072
	s_add_i32 m0, s66, 0xc000
	ds_read_b128 v[156:159], v174
	ds_read_b128 v[160:163], v174 offset:1024
	ds_read_b128 v[180:183], v174 offset:2048
	ds_read_b128 v[184:187], v174 offset:3072
	ds_read_b128 v[188:191], v174 offset:4096
	ds_read_b128 v[192:195], v174 offset:5120
	ds_read_b128 v[222:225], v174 offset:6144
	global_load_lds_dwordx4 v138, s[56:57]
	s_add_i32 m0, s66, 0xe000
	ds_read_b128 v[226:229], v174 offset:7168
	global_load_lds_dwordx4 v136, s[56:57]
	s_waitcnt lgkmcnt(8)
	s_barrier
	s_waitcnt lgkmcnt(0)
	s_waitcnt lgkmcnt(0)
	v_mfma_f32_16x16x32_bf16 v[132:135], v[140:143], v[156:159], v[132:135]
	v_mfma_f32_16x16x32_bf16 v[128:131], v[148:151], v[156:159], v[128:131]
	v_mfma_f32_16x16x32_bf16 v[116:119], v[140:143], v[180:183], v[116:119]
	v_mfma_f32_16x16x32_bf16 v[112:115], v[148:151], v[180:183], v[112:115]
	v_mfma_f32_16x16x32_bf16 v[100:103], v[140:143], v[188:191], v[100:103]
	v_mfma_f32_16x16x32_bf16 v[96:99], v[148:151], v[188:191], v[96:99]
	v_mfma_f32_16x16x32_bf16 v[84:87], v[140:143], v[222:225], v[84:87]
	v_mfma_f32_16x16x32_bf16 v[80:83], v[148:151], v[222:225], v[80:83]
	v_mfma_f32_16x16x32_bf16 v[132:135], v[144:147], v[160:163], v[132:135]
	v_mfma_f32_16x16x32_bf16 v[128:131], v[152:155], v[160:163], v[128:131]
	v_mfma_f32_16x16x32_bf16 v[116:119], v[144:147], v[184:187], v[116:119]
	v_mfma_f32_16x16x32_bf16 v[112:115], v[152:155], v[184:187], v[112:115]
	v_mfma_f32_16x16x32_bf16 v[100:103], v[144:147], v[192:195], v[100:103]
	v_mfma_f32_16x16x32_bf16 v[96:99], v[152:155], v[192:195], v[96:99]
	v_mfma_f32_16x16x32_bf16 v[84:87], v[144:147], v[226:229], v[84:87]
	v_mfma_f32_16x16x32_bf16 v[80:83], v[152:155], v[226:229], v[80:83]
	s_barrier
	s_add_i32 m0, s65, 0x10000
	ds_read_b128 v[230:233], v217 offset:16384
	ds_read_b128 v[234:237], v217 offset:17408
	ds_read_b128 v[238:241], v217 offset:18432
	global_load_lds_dwordx4 v0, s[60:61]
	s_add_i32 m0, s65, 0x12000
	ds_read_b128 v[242:245], v217 offset:19456
	global_load_lds_dwordx4 v2, s[60:61]
	s_barrier
	s_waitcnt lgkmcnt(0)
	s_waitcnt lgkmcnt(0)
	v_mfma_f32_16x16x32_bf16 v[124:127], v[230:233], v[156:159], v[124:127]
	v_mfma_f32_16x16x32_bf16 v[120:123], v[238:241], v[156:159], v[120:123]
	v_mfma_f32_16x16x32_bf16 v[108:111], v[230:233], v[180:183], v[108:111]
	v_mfma_f32_16x16x32_bf16 v[104:107], v[238:241], v[180:183], v[104:107]
	v_mfma_f32_16x16x32_bf16 v[92:95], v[230:233], v[188:191], v[92:95]
	v_mfma_f32_16x16x32_bf16 v[88:91], v[238:241], v[188:191], v[88:91]
	v_mfma_f32_16x16x32_bf16 v[76:79], v[230:233], v[222:225], v[76:79]
	v_mfma_f32_16x16x32_bf16 v[72:75], v[238:241], v[222:225], v[72:75]
	v_mfma_f32_16x16x32_bf16 v[124:127], v[234:237], v[160:163], v[124:127]
	v_mfma_f32_16x16x32_bf16 v[120:123], v[242:245], v[160:163], v[120:123]
	v_mfma_f32_16x16x32_bf16 v[108:111], v[234:237], v[184:187], v[108:111]
	v_mfma_f32_16x16x32_bf16 v[104:107], v[242:245], v[184:187], v[104:107]
	v_mfma_f32_16x16x32_bf16 v[92:95], v[234:237], v[192:195], v[92:95]
	v_mfma_f32_16x16x32_bf16 v[88:91], v[242:245], v[192:195], v[88:91]
	v_mfma_f32_16x16x32_bf16 v[76:79], v[234:237], v[226:229], v[76:79]
	v_mfma_f32_16x16x32_bf16 v[72:75], v[242:245], v[226:229], v[72:75]
	s_mov_b32 m0, s66
	s_barrier
	ds_read_b128 v[156:159], v174 offset:16384
	ds_read_b128 v[160:163], v174 offset:17408
	ds_read_b128 v[180:183], v174 offset:18432
	ds_read_b128 v[184:187], v174 offset:19456
	ds_read_b128 v[188:191], v174 offset:20480
	ds_read_b128 v[192:195], v174 offset:21504
	ds_read_b128 v[222:225], v174 offset:22528
	global_load_lds_dwordx4 v0, s[62:63]
	s_mov_b32 m0, s67
	ds_read_b128 v[226:229], v174 offset:23552
	global_load_lds_dwordx4 v2, s[62:63]
	s_barrier
	s_waitcnt lgkmcnt(0)
	s_waitcnt lgkmcnt(0)
	v_mfma_f32_16x16x32_bf16 v[68:71], v[140:143], v[156:159], v[68:71]
	v_mfma_f32_16x16x32_bf16 v[64:67], v[148:151], v[156:159], v[64:67]
	v_mfma_f32_16x16x32_bf16 v[52:55], v[140:143], v[180:183], v[52:55]
	v_mfma_f32_16x16x32_bf16 v[48:51], v[148:151], v[180:183], v[48:51]
	v_mfma_f32_16x16x32_bf16 v[36:39], v[140:143], v[188:191], v[36:39]
	v_mfma_f32_16x16x32_bf16 v[32:35], v[148:151], v[188:191], v[32:35]
	v_mfma_f32_16x16x32_bf16 v[20:23], v[140:143], v[222:225], v[20:23]
	v_mfma_f32_16x16x32_bf16 v[16:19], v[148:151], v[222:225], v[16:19]
	v_mfma_f32_16x16x32_bf16 v[68:71], v[144:147], v[160:163], v[68:71]
	v_mfma_f32_16x16x32_bf16 v[64:67], v[152:155], v[160:163], v[64:67]
	v_mfma_f32_16x16x32_bf16 v[52:55], v[144:147], v[184:187], v[52:55]
	v_mfma_f32_16x16x32_bf16 v[48:51], v[152:155], v[184:187], v[48:51]
	v_mfma_f32_16x16x32_bf16 v[36:39], v[144:147], v[192:195], v[36:39]
	v_mfma_f32_16x16x32_bf16 v[32:35], v[152:155], v[192:195], v[32:35]
	v_mfma_f32_16x16x32_bf16 v[20:23], v[144:147], v[226:229], v[20:23]
	v_mfma_f32_16x16x32_bf16 v[16:19], v[152:155], v[226:229], v[16:19]
	s_barrier
	s_add_i32 m0, s65, 0x14000
	s_add_u32 s56, s60, 0x100000
	s_addc_u32 s57, s61, 0
	global_load_lds_dwordx4 v0, s[56:57]
	s_add_i32 m0, s65, 0x16000
	s_add_u32 s98, s62, 0x100000
	s_addc_u32 s99, s63, 0
	global_load_lds_dwordx4 v2, s[56:57]
	s_waitcnt vmcnt(6)
	s_barrier
; #define G_STAGE(bufoff, gbase) do { _Pragma("unroll") for (int _i = 0; _i < 2; ++_i) \
;         __builtin_amdgcn_global_load_lds((const unsigned*)((const char*)(gbase) + voff[_i]), (LAS unsigned*)(lds + (bufoff) + ldsw + _i * 8192), 16, 0, 0); } while (0)
; #define G_LDA(dst, b, h) do { _Pragma("unroll") for (int m = 0; m < 4; ++m) _Pragma("unroll") for (int k = 0; k < 2; ++k) dst[m][k] = *(const LAS bf16x8*)(lds + G_SA(b, h) + aoff + m * 2048 + k * 1024); } while (0)
; #define G_LDB(dst, b, h) do { _Pragma("unroll") for (int n = 0; n < 2; ++n) _Pragma("unroll") for (int k = 0; k < 2; ++k) dst[n][k] = *(const LAS bf16x8*)(lds + G_SB(b, h) + boff + n * 2048 + k * 1024); } while (0)
; #define G_MMA(ai, bj, At, Bt) do { __builtin_amdgcn_s_setprio(1); _Pragma("unroll") for (int m = 0; m < 4; ++m) _Pragma("unroll") for (int n = 0; n < 2; ++n) _Pragma("unroll") for (int k = 0; k < 2; ++k) \
;         acc[ai][bj][m][n] = MFMA16(Bt[n][k], At[m][k], acc[ai][bj][m][n]); __builtin_amdgcn_s_setprio(0); } while (0)
; #define G_WAIT_V(n) asm volatile("s_waitcnt vmcnt(" #n ")" ::: "memory")
; #define G_WAIT_L(n) asm volatile("s_waitcnt lgkmcnt(" #n ")" ::: "memory")
; #define G_BAR __builtin_amdgcn_s_barrier()
; #define G_SCHED __builtin_amdgcn_sched_barrier(0)
; template <class Epi>
; __device__ __forceinline__ void gemm_phase(LAS unsigned char* lds, const bf16_t* Ag, const bf16_t* Btg, const int K, const int nM, const int nN, const Epi& E) {
;     ...
;         for (int t = 0; t < nt; t += 2) {
;             const bool last = (t == nt - 2);
;             const char* a1 = cA + (size_t)(t + 1) * kstep;
;             const char* a2 = last ? nA : cA + (size_t)(t + 2) * kstep; const char* b2 = last ? nB : cB + (size_t)(t + 2) * kstep;
;             const char* a3 = a2 + kstep; const char* b3 = b2 + kstep;
;     ...
;             G_WAIT_V(6); G_BAR; G_MMA(1, 1, At, B1); G_BAR;
;             G_LDB(B0, 1, 0); G_SCHED; G_LDA(At, 1, 0); G_STAGE(G_SA(0, 1), a2 + hstep);
;             G_WAIT_L(8); G_BAR; G_WAIT_L(0); G_MMA(0, 0, At, B0); G_BAR; G_SCHED;
;             G_LDB(B1, 1, 1); G_STAGE(G_SB(1, 0), b3);
;             G_BAR; G_WAIT_L(0); G_MMA(0, 1, At, B1); G_BAR;
;             G_LDA(At, 1, 1); G_STAGE(G_SA(1, 0), a3);
;             G_BAR; G_WAIT_L(0); G_MMA(1, 0, At, B0); G_BAR; G_SCHED;
;             G_STAGE(G_SB(1, 1), b3 + hstep);
	v_mfma_f32_16x16x32_bf16 v[60:63], v[230:233], v[156:159], v[60:63]
	v_mfma_f32_16x16x32_bf16 v[56:59], v[238:241], v[156:159], v[56:59]
	v_mfma_f32_16x16x32_bf16 v[44:47], v[230:233], v[180:183], v[44:47]
	v_mfma_f32_16x16x32_bf16 v[40:43], v[238:241], v[180:183], v[40:43]
	v_mfma_f32_16x16x32_bf16 v[28:31], v[230:233], v[188:191], v[28:31]
	v_mfma_f32_16x16x32_bf16 v[24:27], v[238:241], v[188:191], v[24:27]
	v_mfma_f32_16x16x32_bf16 v[12:15], v[230:233], v[222:225], v[12:15]
	v_mfma_f32_16x16x32_bf16 v[8:11], v[238:241], v[222:225], v[8:11]
	v_mfma_f32_16x16x32_bf16 v[60:63], v[234:237], v[160:163], v[60:63]
	v_mfma_f32_16x16x32_bf16 v[56:59], v[242:245], v[160:163], v[56:59]
	v_mfma_f32_16x16x32_bf16 v[44:47], v[234:237], v[184:187], v[44:47]
	v_mfma_f32_16x16x32_bf16 v[40:43], v[242:245], v[184:187], v[40:43]
	v_mfma_f32_16x16x32_bf16 v[28:31], v[234:237], v[192:195], v[28:31]
	v_mfma_f32_16x16x32_bf16 v[24:27], v[242:245], v[192:195], v[24:27]
	v_mfma_f32_16x16x32_bf16 v[12:15], v[234:237], v[226:229], v[12:15]
	v_mfma_f32_16x16x32_bf16 v[8:11], v[242:245], v[226:229], v[8:11]
	s_barrier
	ds_read_b128 v[140:143], v217 offset:32768
	ds_read_b128 v[144:147], v217 offset:33792
	ds_read_b128 v[148:151], v217 offset:34816
	ds_read_b128 v[152:155], v217 offset:35840
	s_mov_b32 m0, s68
	ds_read_b128 v[156:159], v174 offset:32768
	ds_read_b128 v[160:163], v174 offset:33792
	ds_read_b128 v[180:183], v174 offset:34816
	ds_read_b128 v[184:187], v174 offset:35840
	ds_read_b128 v[188:191], v174 offset:36864
	ds_read_b128 v[192:195], v174 offset:37888
	ds_read_b128 v[222:225], v174 offset:38912
	global_load_lds_dwordx4 v0, s[98:99]
	s_mov_b32 m0, s69
	ds_read_b128 v[226:229], v174 offset:39936
	global_load_lds_dwordx4 v2, s[98:99]
	s_waitcnt lgkmcnt(8)
	s_barrier
	s_waitcnt lgkmcnt(0)
	s_waitcnt lgkmcnt(0)
	v_mfma_f32_16x16x32_bf16 v[132:135], v[140:143], v[156:159], v[132:135]
	v_mfma_f32_16x16x32_bf16 v[128:131], v[148:151], v[156:159], v[128:131]
	v_mfma_f32_16x16x32_bf16 v[116:119], v[140:143], v[180:183], v[116:119]
	v_mfma_f32_16x16x32_bf16 v[112:115], v[148:151], v[180:183], v[112:115]
	v_mfma_f32_16x16x32_bf16 v[100:103], v[140:143], v[188:191], v[100:103]
	v_mfma_f32_16x16x32_bf16 v[96:99], v[148:151], v[188:191], v[96:99]
	v_mfma_f32_16x16x32_bf16 v[84:87], v[140:143], v[222:225], v[84:87]
	v_mfma_f32_16x16x32_bf16 v[80:83], v[148:151], v[222:225], v[80:83]
	v_mfma_f32_16x16x32_bf16 v[132:135], v[144:147], v[160:163], v[132:135]
	v_mfma_f32_16x16x32_bf16 v[128:131], v[152:155], v[160:163], v[128:131]
	v_mfma_f32_16x16x32_bf16 v[116:119], v[144:147], v[184:187], v[116:119]
	v_mfma_f32_16x16x32_bf16 v[112:115], v[152:155], v[184:187], v[112:115]
	v_mfma_f32_16x16x32_bf16 v[100:103], v[144:147], v[192:195], v[100:103]
	v_mfma_f32_16x16x32_bf16 v[96:99], v[152:155], v[192:195], v[96:99]
	v_mfma_f32_16x16x32_bf16 v[84:87], v[144:147], v[226:229], v[84:87]
	v_mfma_f32_16x16x32_bf16 v[80:83], v[152:155], v[226:229], v[80:83]
	s_barrier
	s_add_i32 m0, s65, 0x18000
	ds_read_b128 v[230:233], v217 offset:49152
	ds_read_b128 v[234:237], v217 offset:50176
	ds_read_b128 v[238:241], v217 offset:51200
	s_add_u32 s98, s60, 0x80
	s_addc_u32 s99, s61, 0
	global_load_lds_dwordx4 v0, s[98:99]
	s_add_i32 m0, s65, 0x1a000
	ds_read_b128 v[242:245], v217 offset:52224
	global_load_lds_dwordx4 v2, s[98:99]
	s_barrier
	s_waitcnt lgkmcnt(0)
	s_waitcnt lgkmcnt(0)
	v_mfma_f32_16x16x32_bf16 v[124:127], v[230:233], v[156:159], v[124:127]
	v_mfma_f32_16x16x32_bf16 v[120:123], v[238:241], v[156:159], v[120:123]
	v_mfma_f32_16x16x32_bf16 v[108:111], v[230:233], v[180:183], v[108:111]
	v_mfma_f32_16x16x32_bf16 v[104:107], v[238:241], v[180:183], v[104:107]
	v_mfma_f32_16x16x32_bf16 v[92:95], v[230:233], v[188:191], v[92:95]
	v_mfma_f32_16x16x32_bf16 v[88:91], v[238:241], v[188:191], v[88:91]
	v_mfma_f32_16x16x32_bf16 v[76:79], v[230:233], v[222:225], v[76:79]
	v_mfma_f32_16x16x32_bf16 v[72:75], v[238:241], v[222:225], v[72:75]
	v_mfma_f32_16x16x32_bf16 v[124:127], v[234:237], v[160:163], v[124:127]
	v_mfma_f32_16x16x32_bf16 v[120:123], v[242:245], v[160:163], v[120:123]
	v_mfma_f32_16x16x32_bf16 v[108:111], v[234:237], v[184:187], v[108:111]
	v_mfma_f32_16x16x32_bf16 v[104:107], v[242:245], v[184:187], v[104:107]
	v_mfma_f32_16x16x32_bf16 v[92:95], v[234:237], v[192:195], v[92:95]
	v_mfma_f32_16x16x32_bf16 v[88:91], v[242:245], v[192:195], v[88:91]
	v_mfma_f32_16x16x32_bf16 v[76:79], v[234:237], v[226:229], v[76:79]
	v_mfma_f32_16x16x32_bf16 v[72:75], v[242:245], v[226:229], v[72:75]
	s_mov_b32 m0, s70
	s_barrier
	ds_read_b128 v[156:159], v174 offset:49152
	ds_read_b128 v[160:163], v174 offset:50176
	ds_read_b128 v[180:183], v174 offset:51200
	ds_read_b128 v[184:187], v174 offset:52224
	ds_read_b128 v[188:191], v174 offset:53248
	ds_read_b128 v[192:195], v174 offset:54272
	ds_read_b128 v[222:225], v174 offset:55296
	s_add_u32 s98, s62, 0x80
	s_addc_u32 s99, s63, 0
	global_load_lds_dwordx4 v0, s[98:99]
	s_mov_b32 m0, s71
	ds_read_b128 v[226:229], v174 offset:56320
	global_load_lds_dwordx4 v2, s[98:99]
	s_barrier
	s_waitcnt lgkmcnt(0)
	s_waitcnt lgkmcnt(0)
	v_mfma_f32_16x16x32_bf16 v[68:71], v[140:143], v[156:159], v[68:71]
	v_mfma_f32_16x16x32_bf16 v[64:67], v[148:151], v[156:159], v[64:67]
	v_mfma_f32_16x16x32_bf16 v[52:55], v[140:143], v[180:183], v[52:55]
	v_mfma_f32_16x16x32_bf16 v[48:51], v[148:151], v[180:183], v[48:51]
	v_mfma_f32_16x16x32_bf16 v[36:39], v[140:143], v[188:191], v[36:39]
	v_mfma_f32_16x16x32_bf16 v[32:35], v[148:151], v[188:191], v[32:35]
	v_mfma_f32_16x16x32_bf16 v[20:23], v[140:143], v[222:225], v[20:23]
	v_mfma_f32_16x16x32_bf16 v[16:19], v[148:151], v[222:225], v[16:19]
	v_mfma_f32_16x16x32_bf16 v[68:71], v[144:147], v[160:163], v[68:71]
	v_mfma_f32_16x16x32_bf16 v[64:67], v[152:155], v[160:163], v[64:67]
	v_mfma_f32_16x16x32_bf16 v[52:55], v[144:147], v[184:187], v[52:55]
	v_mfma_f32_16x16x32_bf16 v[48:51], v[152:155], v[184:187], v[48:51]
	v_mfma_f32_16x16x32_bf16 v[36:39], v[144:147], v[192:195], v[36:39]
	v_mfma_f32_16x16x32_bf16 v[32:35], v[152:155], v[192:195], v[32:35]
	v_mfma_f32_16x16x32_bf16 v[20:23], v[144:147], v[226:229], v[20:23]
	v_mfma_f32_16x16x32_bf16 v[16:19], v[152:155], v[226:229], v[16:19]
	s_barrier
	s_add_i32 m0, s65, 0x1c000
	s_add_u32 s56, s60, 0x100080
	s_addc_u32 s57, s61, 0
	global_load_lds_dwordx4 v0, s[56:57]
	s_add_i32 m0, s65, 0x1e000
	s_add_i32 s79, s79, 2
	global_load_lds_dwordx4 v2, s[56:57]
	s_add_u32 s77, s77, 0x100
	s_addc_u32 s78, s78, 0
	s_mov_b64 s[56:57], s[58:59]
	s_cmp_gt_u32 s79, 61
	s_cbranch_scc1 .LrotX_744
	s_cmp_lg_u32 s79, 60
	s_cselect_b64 s[60:61], -1, 0
	s_add_u32 s58, s56, 0x100
	s_addc_u32 s59, s57, 0
	s_and_b64 s[60:61], s[60:61], exec
	s_cselect_b32 s63, s59, s47
	s_cselect_b32 s62, s58, s46
	s_cselect_b32 s61, s78, s15
	s_cselect_b32 s60, s77, s49

; #define G_STAGE(bufoff, gbase) do { _Pragma("unroll") for (int _i = 0; _i < 2; ++_i) \
;         __builtin_amdgcn_global_load_lds((const unsigned*)((const char*)(gbase) + voff[_i]), (LAS unsigned*)(lds + (bufoff) + ldsw + _i * 8192), 16, 0, 0); } while (0)
; #define G_LDA(dst, b, h) do { _Pragma("unroll") for (int m = 0; m < 4; ++m) _Pragma("unroll") for (int k = 0; k < 2; ++k) dst[m][k] = *(const LAS bf16x8*)(lds + G_SA(b, h) + aoff + m * 2048 + k * 1024); } while (0)
; #define G_LDB(dst, b, h) do { _Pragma("unroll") for (int n = 0; n < 2; ++n) _Pragma("unroll") for (int k = 0; k < 2; ++k) dst[n][k] = *(const LAS bf16x8*)(lds + G_SB(b, h) + boff + n * 2048 + k * 1024); } while (0)
; #define G_MMA(ai, bj, At, Bt) do { __builtin_amdgcn_s_setprio(1); _Pragma("unroll") for (int m = 0; m < 4; ++m) _Pragma("unroll") for (int n = 0; n < 2; ++n) _Pragma("unroll") for (int k = 0; k < 2; ++k) \
;         acc[ai][bj][m][n] = MFMA16(Bt[n][k], At[m][k], acc[ai][bj][m][n]); __builtin_amdgcn_s_setprio(0); } while (0)
; #define G_WAIT_V(n) asm volatile("s_waitcnt vmcnt(" #n ")" ::: "memory")
; #define G_WAIT_L(n) asm volatile("s_waitcnt lgkmcnt(" #n ")" ::: "memory")
; #define G_BAR __builtin_amdgcn_s_barrier()
; #define G_SCHED __builtin_amdgcn_sched_barrier(0)
; template <class Epi>
; __device__ __forceinline__ void gemm_phase(LAS unsigned char* lds, const bf16_t* Ag, const bf16_t* Btg, const int K, const int nM, const int nN, const Epi& E) {
;     ...
;             G_LDB(B0, 0, 0); G_SCHED; G_LDA(At, 0, 0); G_STAGE(G_SA(1, 1), a1 + hstep);
;             G_WAIT_L(8); G_BAR; G_WAIT_L(0); G_MMA(0, 0, At, B0); G_BAR; G_SCHED;
;             G_LDB(B1, 0, 1); G_STAGE(G_SB(0, 0), b2);
;             G_BAR; G_WAIT_L(0); G_MMA(0, 1, At, B1); G_BAR;
;             G_LDA(At, 0, 1); G_STAGE(G_SA(0, 0), a2);
;             G_BAR; G_WAIT_L(0); G_MMA(1, 0, At, B0); G_BAR; G_SCHED;
;             G_STAGE(G_SB(0, 1), b2 + hstep);
;             G_WAIT_V(6); G_BAR; G_MMA(1, 1, At, B1); G_BAR;
.LmainW_848:
	ds_read_b128 v[130:133], v217
	ds_read_b128 v[134:137], v217 offset:1024
	ds_read_b128 v[144:147], v217 offset:2048
	ds_read_b128 v[148:151], v217 offset:3072
	s_add_i32 m0, s60, 0xc000
	ds_read_b128 v[156:159], v222
	ds_read_b128 v[160:163], v222 offset:1024
	ds_read_b128 v[164:167], v222 offset:2048
	ds_read_b128 v[180:183], v222 offset:3072
	ds_read_b128 v[184:187], v222 offset:4096
	ds_read_b128 v[224:227], v222 offset:5120
	ds_read_b128 v[228:231], v222 offset:6144
	global_load_lds_dwordx4 v170, s[50:51]
	s_add_i32 m0, s60, 0xe000
	ds_read_b128 v[232:235], v222 offset:7168
	global_load_lds_dwordx4 v168, s[50:51]
	s_waitcnt lgkmcnt(8)
	s_barrier
	s_waitcnt lgkmcnt(0)
	s_waitcnt lgkmcnt(0)
	v_mfma_f32_16x16x32_bf16 v[152:155], v[130:133], v[156:159], v[152:155]
	v_mfma_f32_16x16x32_bf16 v[138:141], v[144:147], v[156:159], v[140:143]
	v_mfma_f32_16x16x32_bf16 v[116:119], v[130:133], v[164:167], v[116:119]
	v_mfma_f32_16x16x32_bf16 v[112:115], v[144:147], v[164:167], v[112:115]
	v_mfma_f32_16x16x32_bf16 v[100:103], v[130:133], v[184:187], v[100:103]
	v_mfma_f32_16x16x32_bf16 v[96:99], v[144:147], v[184:187], v[96:99]
	v_mfma_f32_16x16x32_bf16 v[84:87], v[130:133], v[228:231], v[84:87]
	v_mfma_f32_16x16x32_bf16 v[80:83], v[144:147], v[228:231], v[80:83]
	v_mfma_f32_16x16x32_bf16 v[152:155], v[134:137], v[160:163], v[152:155]
	v_mfma_f32_16x16x32_bf16 v[138:141], v[148:151], v[160:163], v[138:141]
	v_mfma_f32_16x16x32_bf16 v[116:119], v[134:137], v[180:183], v[116:119]
	v_mfma_f32_16x16x32_bf16 v[112:115], v[148:151], v[180:183], v[112:115]
	v_mfma_f32_16x16x32_bf16 v[100:103], v[134:137], v[224:227], v[100:103]
	v_mfma_f32_16x16x32_bf16 v[96:99], v[148:151], v[224:227], v[96:99]
	v_mfma_f32_16x16x32_bf16 v[84:87], v[134:137], v[232:235], v[84:87]
	v_mfma_f32_16x16x32_bf16 v[80:83], v[148:151], v[232:235], v[80:83]
	s_barrier
	s_add_i32 s73, 0, 0x14000
	s_add_i32 m0, s59, 0x10000
	ds_read_b128 v[236:239], v217 offset:16384
	ds_read_b128 v[240:243], v217 offset:17408
	ds_read_b128 v[244:247], v217 offset:18432
	global_load_lds_dwordx4 v0, s[52:53]
	s_add_i32 m0, s59, 0x12000
	ds_read_b128 v[248:251], v217 offset:19456
	global_load_lds_dwordx4 v2, s[52:53]
	s_barrier
	s_waitcnt lgkmcnt(0)
	s_waitcnt lgkmcnt(0)
	v_mfma_f32_16x16x32_bf16 v[124:127], v[236:239], v[156:159], v[124:127]
	v_mfma_f32_16x16x32_bf16 v[120:123], v[244:247], v[156:159], v[120:123]
	v_mfma_f32_16x16x32_bf16 v[108:111], v[236:239], v[164:167], v[108:111]
	v_mfma_f32_16x16x32_bf16 v[104:107], v[244:247], v[164:167], v[104:107]
	v_mfma_f32_16x16x32_bf16 v[92:95], v[236:239], v[184:187], v[92:95]
	v_mfma_f32_16x16x32_bf16 v[88:91], v[244:247], v[184:187], v[88:91]
	v_mfma_f32_16x16x32_bf16 v[76:79], v[236:239], v[228:231], v[76:79]
	v_mfma_f32_16x16x32_bf16 v[72:75], v[244:247], v[228:231], v[72:75]
	v_mfma_f32_16x16x32_bf16 v[124:127], v[240:243], v[160:163], v[124:127]
	v_mfma_f32_16x16x32_bf16 v[120:123], v[248:251], v[160:163], v[120:123]
	v_mfma_f32_16x16x32_bf16 v[108:111], v[240:243], v[180:183], v[108:111]
	v_mfma_f32_16x16x32_bf16 v[104:107], v[248:251], v[180:183], v[104:107]
	v_mfma_f32_16x16x32_bf16 v[92:95], v[240:243], v[224:227], v[92:95]
	v_mfma_f32_16x16x32_bf16 v[88:91], v[248:251], v[224:227], v[88:91]
	v_mfma_f32_16x16x32_bf16 v[76:79], v[240:243], v[232:235], v[76:79]
	v_mfma_f32_16x16x32_bf16 v[72:75], v[248:251], v[232:235], v[72:75]
	s_mov_b32 m0, s60
	s_add_u32 s76, s54, 0x80
	s_addc_u32 s77, s55, 0
	s_barrier
	ds_read_b128 v[156:159], v222 offset:16384
	ds_read_b128 v[160:163], v222 offset:17408
	ds_read_b128 v[164:167], v222 offset:18432
	ds_read_b128 v[180:183], v222 offset:19456
	ds_read_b128 v[184:187], v222 offset:20480
	ds_read_b128 v[224:227], v222 offset:21504
	ds_read_b128 v[228:231], v222 offset:22528
	ds_read_b128 v[232:235], v222 offset:23552
	global_load_lds_dwordx4 v0, s[54:55]
	s_add_u32 s76, s54, 0x80
	s_mov_b32 m0, s61
	s_addc_u32 s77, s55, 0
	global_load_lds_dwordx4 v2, s[54:55]
	s_barrier
	s_waitcnt lgkmcnt(0)
	s_waitcnt lgkmcnt(0)
	v_mfma_f32_16x16x32_bf16 v[60:63], v[130:133], v[156:159], v[60:63]
	v_mfma_f32_16x16x32_bf16 v[56:59], v[144:147], v[156:159], v[56:59]
	v_mfma_f32_16x16x32_bf16 v[44:47], v[130:133], v[164:167], v[44:47]
	v_mfma_f32_16x16x32_bf16 v[40:43], v[144:147], v[164:167], v[40:43]
	v_mfma_f32_16x16x32_bf16 v[28:31], v[130:133], v[184:187], v[28:31]
	v_mfma_f32_16x16x32_bf16 v[24:27], v[144:147], v[184:187], v[24:27]
	v_mfma_f32_16x16x32_bf16 v[12:15], v[130:133], v[228:231], v[12:15]
	v_mfma_f32_16x16x32_bf16 v[8:11], v[144:147], v[228:231], v[8:11]
	v_mfma_f32_16x16x32_bf16 v[60:63], v[134:137], v[160:163], v[60:63]
	v_mfma_f32_16x16x32_bf16 v[56:59], v[148:151], v[160:163], v[56:59]
	v_mfma_f32_16x16x32_bf16 v[44:47], v[134:137], v[180:183], v[44:47]
	v_mfma_f32_16x16x32_bf16 v[40:43], v[148:151], v[180:183], v[40:43]
	v_mfma_f32_16x16x32_bf16 v[28:31], v[134:137], v[224:227], v[28:31]
	v_mfma_f32_16x16x32_bf16 v[24:27], v[148:151], v[224:227], v[24:27]
	v_mfma_f32_16x16x32_bf16 v[12:15], v[134:137], v[232:235], v[12:15]
	v_mfma_f32_16x16x32_bf16 v[8:11], v[148:151], v[232:235], v[8:11]
	s_barrier
	s_add_i32 m0, s59, 0x14000
	s_add_u32 s74, s52, 0x40000
	s_addc_u32 s75, s53, 0
	global_load_lds_dwordx4 v0, s[74:75]
	s_add_i32 m0, s59, 0x16000
	s_add_u32 s54, s54, 0x40000
	s_addc_u32 s55, s55, 0
	global_load_lds_dwordx4 v2, s[74:75]
	s_waitcnt vmcnt(6)
	s_barrier
; #define G_STAGE(bufoff, gbase) do { _Pragma("unroll") for (int _i = 0; _i < 2; ++_i) \
;         __builtin_amdgcn_global_load_lds((const unsigned*)((const char*)(gbase) + voff[_i]), (LAS unsigned*)(lds + (bufoff) + ldsw + _i * 8192), 16, 0, 0); } while (0)
; #define G_LDA(dst, b, h) do { _Pragma("unroll") for (int m = 0; m < 4; ++m) _Pragma("unroll") for (int k = 0; k < 2; ++k) dst[m][k] = *(const LAS bf16x8*)(lds + G_SA(b, h) + aoff + m * 2048 + k * 1024); } while (0)
; #define G_LDB(dst, b, h) do { _Pragma("unroll") for (int n = 0; n < 2; ++n) _Pragma("unroll") for (int k = 0; k < 2; ++k) dst[n][k] = *(const LAS bf16x8*)(lds + G_SB(b, h) + boff + n * 2048 + k * 1024); } while (0)
; #define G_MMA(ai, bj, At, Bt) do { __builtin_amdgcn_s_setprio(1); _Pragma("unroll") for (int m = 0; m < 4; ++m) _Pragma("unroll") for (int n = 0; n < 2; ++n) _Pragma("unroll") for (int k = 0; k < 2; ++k) \
;         acc[ai][bj][m][n] = MFMA16(Bt[n][k], At[m][k], acc[ai][bj][m][n]); __builtin_amdgcn_s_setprio(0); } while (0)
; #define G_WAIT_V(n) asm volatile("s_waitcnt vmcnt(" #n ")" ::: "memory")
; #define G_WAIT_L(n) asm volatile("s_waitcnt lgkmcnt(" #n ")" ::: "memory")
; #define G_BAR __builtin_amdgcn_s_barrier()
; #define G_SCHED __builtin_amdgcn_sched_barrier(0)
; template <class Epi>
; __device__ __forceinline__ void gemm_phase(LAS unsigned char* lds, const bf16_t* Ag, const bf16_t* Btg, const int K, const int nM, const int nN, const Epi& E) {
;     ...
;         for (int t = 0; t < nt; t += 2) {
;             const bool last = (t == nt - 2);
;             const char* a1 = cA + (size_t)(t + 1) * kstep;
;             const char* a2 = last ? nA : cA + (size_t)(t + 2) * kstep; const char* b2 = last ? nB : cB + (size_t)(t + 2) * kstep;
;             const char* a3 = a2 + kstep; const char* b3 = b2 + kstep;
;     ...
;             G_WAIT_V(6); G_BAR; G_MMA(1, 1, At, B1); G_BAR;
;             G_LDB(B0, 1, 0); G_SCHED; G_LDA(At, 1, 0); G_STAGE(G_SA(0, 1), a2 + hstep);
;             G_WAIT_L(8); G_BAR; G_WAIT_L(0); G_MMA(0, 0, At, B0); G_BAR; G_SCHED;
;             G_LDB(B1, 1, 1); G_STAGE(G_SB(1, 0), b3);
;             G_BAR; G_WAIT_L(0); G_MMA(0, 1, At, B1); G_BAR;
;             G_LDA(At, 1, 1); G_STAGE(G_SA(1, 0), a3);
;             G_BAR; G_WAIT_L(0); G_MMA(1, 0, At, B0); G_BAR; G_SCHED;
;             G_STAGE(G_SB(1, 1), b3 + hstep);
	v_mfma_f32_16x16x32_bf16 v[68:71], v[236:239], v[156:159], v[68:71]
	v_mfma_f32_16x16x32_bf16 v[64:67], v[244:247], v[156:159], v[64:67]
	v_mfma_f32_16x16x32_bf16 v[52:55], v[236:239], v[164:167], v[52:55]
	v_mfma_f32_16x16x32_bf16 v[48:51], v[244:247], v[164:167], v[48:51]
	v_mfma_f32_16x16x32_bf16 v[36:39], v[236:239], v[184:187], v[36:39]
	v_mfma_f32_16x16x32_bf16 v[32:35], v[244:247], v[184:187], v[32:35]
	v_mfma_f32_16x16x32_bf16 v[20:23], v[236:239], v[228:231], v[20:23]
	v_mfma_f32_16x16x32_bf16 v[16:19], v[244:247], v[228:231], v[16:19]
	v_mfma_f32_16x16x32_bf16 v[68:71], v[240:243], v[160:163], v[68:71]
	v_mfma_f32_16x16x32_bf16 v[64:67], v[248:251], v[160:163], v[64:67]
	v_mfma_f32_16x16x32_bf16 v[52:55], v[240:243], v[180:183], v[52:55]
	v_mfma_f32_16x16x32_bf16 v[48:51], v[248:251], v[180:183], v[48:51]
	v_mfma_f32_16x16x32_bf16 v[36:39], v[240:243], v[224:227], v[36:39]
	v_mfma_f32_16x16x32_bf16 v[32:35], v[248:251], v[224:227], v[32:35]
	v_mfma_f32_16x16x32_bf16 v[20:23], v[240:243], v[232:235], v[20:23]
	v_mfma_f32_16x16x32_bf16 v[16:19], v[248:251], v[232:235], v[16:19]
	s_barrier
	ds_read_b128 v[130:133], v217 offset:32768
	ds_read_b128 v[134:137], v217 offset:33792
	ds_read_b128 v[144:147], v217 offset:34816
	ds_read_b128 v[148:151], v217 offset:35840
	s_mov_b32 m0, s62
	ds_read_b128 v[156:159], v222 offset:32768
	ds_read_b128 v[160:163], v222 offset:33792
	ds_read_b128 v[164:167], v222 offset:34816
	ds_read_b128 v[180:183], v222 offset:35840
	ds_read_b128 v[184:187], v222 offset:36864
	ds_read_b128 v[224:227], v222 offset:37888
	ds_read_b128 v[228:231], v222 offset:38912
	global_load_lds_dwordx4 v0, s[54:55]
	s_mov_b32 m0, s63
	ds_read_b128 v[232:235], v222 offset:39936
	global_load_lds_dwordx4 v2, s[54:55]
	s_waitcnt lgkmcnt(8)
	s_barrier
	s_waitcnt lgkmcnt(0)
	s_waitcnt lgkmcnt(0)
	v_mfma_f32_16x16x32_bf16 v[152:155], v[130:133], v[156:159], v[152:155]
	v_mfma_f32_16x16x32_bf16 v[138:141], v[144:147], v[156:159], v[138:141]
	v_mfma_f32_16x16x32_bf16 v[116:119], v[130:133], v[164:167], v[116:119]
	v_mfma_f32_16x16x32_bf16 v[112:115], v[144:147], v[164:167], v[112:115]
	v_mfma_f32_16x16x32_bf16 v[100:103], v[130:133], v[184:187], v[100:103]
	v_mfma_f32_16x16x32_bf16 v[96:99], v[144:147], v[184:187], v[96:99]
	v_mfma_f32_16x16x32_bf16 v[84:87], v[130:133], v[228:231], v[84:87]
	v_mfma_f32_16x16x32_bf16 v[80:83], v[144:147], v[228:231], v[80:83]
	v_mfma_f32_16x16x32_bf16 v[152:155], v[134:137], v[160:163], v[152:155]
	v_mfma_f32_16x16x32_bf16 v[140:143], v[148:151], v[160:163], v[138:141]
	v_mfma_f32_16x16x32_bf16 v[116:119], v[134:137], v[180:183], v[116:119]
	v_mfma_f32_16x16x32_bf16 v[112:115], v[148:151], v[180:183], v[112:115]
	v_mfma_f32_16x16x32_bf16 v[100:103], v[134:137], v[224:227], v[100:103]
	v_mfma_f32_16x16x32_bf16 v[96:99], v[148:151], v[224:227], v[96:99]
	v_mfma_f32_16x16x32_bf16 v[84:87], v[134:137], v[232:235], v[84:87]
	v_mfma_f32_16x16x32_bf16 v[80:83], v[148:151], v[232:235], v[80:83]
	s_barrier
	s_add_i32 m0, s59, 0x18000
	ds_read_b128 v[236:239], v217 offset:49152
	ds_read_b128 v[240:243], v217 offset:50176
	ds_read_b128 v[244:247], v217 offset:51200
	s_add_u32 s98, s52, 0x80
	s_addc_u32 s99, s53, 0
	global_load_lds_dwordx4 v0, s[98:99]
	s_add_i32 m0, s59, 0x1a000
	ds_read_b128 v[248:251], v217 offset:52224
	global_load_lds_dwordx4 v2, s[98:99]
	s_barrier
	s_waitcnt lgkmcnt(0)
	s_waitcnt lgkmcnt(0)
	v_mfma_f32_16x16x32_bf16 v[124:127], v[236:239], v[156:159], v[124:127]
	v_mfma_f32_16x16x32_bf16 v[120:123], v[244:247], v[156:159], v[120:123]
	v_mfma_f32_16x16x32_bf16 v[108:111], v[236:239], v[164:167], v[108:111]
	v_mfma_f32_16x16x32_bf16 v[104:107], v[244:247], v[164:167], v[104:107]
	v_mfma_f32_16x16x32_bf16 v[92:95], v[236:239], v[184:187], v[92:95]
	v_mfma_f32_16x16x32_bf16 v[88:91], v[244:247], v[184:187], v[88:91]
	v_mfma_f32_16x16x32_bf16 v[76:79], v[236:239], v[228:231], v[76:79]
	v_mfma_f32_16x16x32_bf16 v[72:75], v[244:247], v[228:231], v[72:75]
	v_mfma_f32_16x16x32_bf16 v[124:127], v[240:243], v[160:163], v[124:127]
	v_mfma_f32_16x16x32_bf16 v[120:123], v[248:251], v[160:163], v[120:123]
	v_mfma_f32_16x16x32_bf16 v[108:111], v[240:243], v[180:183], v[108:111]
	v_mfma_f32_16x16x32_bf16 v[104:107], v[248:251], v[180:183], v[104:107]
	v_mfma_f32_16x16x32_bf16 v[92:95], v[240:243], v[224:227], v[92:95]
	v_mfma_f32_16x16x32_bf16 v[88:91], v[248:251], v[224:227], v[88:91]
	v_mfma_f32_16x16x32_bf16 v[76:79], v[240:243], v[232:235], v[76:79]
	v_mfma_f32_16x16x32_bf16 v[72:75], v[248:251], v[232:235], v[72:75]
	s_mov_b32 m0, s64
	s_barrier
	ds_read_b128 v[156:159], v222 offset:49152
	ds_read_b128 v[160:163], v222 offset:50176
	ds_read_b128 v[164:167], v222 offset:51200
	ds_read_b128 v[180:183], v222 offset:52224
	ds_read_b128 v[184:187], v222 offset:53248
	ds_read_b128 v[224:227], v222 offset:54272
	ds_read_b128 v[228:231], v222 offset:55296
	global_load_lds_dwordx4 v0, s[76:77]
	s_mov_b32 m0, s65
	ds_read_b128 v[232:235], v222 offset:56320
	global_load_lds_dwordx4 v2, s[76:77]
	s_barrier
	s_waitcnt lgkmcnt(0)
	s_waitcnt lgkmcnt(0)
	v_mfma_f32_16x16x32_bf16 v[60:63], v[130:133], v[156:159], v[60:63]
	v_mfma_f32_16x16x32_bf16 v[56:59], v[144:147], v[156:159], v[56:59]
	v_mfma_f32_16x16x32_bf16 v[44:47], v[130:133], v[164:167], v[44:47]
	v_mfma_f32_16x16x32_bf16 v[40:43], v[144:147], v[164:167], v[40:43]
	v_mfma_f32_16x16x32_bf16 v[28:31], v[130:133], v[184:187], v[28:31]
	v_mfma_f32_16x16x32_bf16 v[24:27], v[144:147], v[184:187], v[24:27]
	v_mfma_f32_16x16x32_bf16 v[12:15], v[130:133], v[228:231], v[12:15]
	v_mfma_f32_16x16x32_bf16 v[8:11], v[144:147], v[228:231], v[8:11]
	v_mfma_f32_16x16x32_bf16 v[60:63], v[134:137], v[160:163], v[60:63]
	v_mfma_f32_16x16x32_bf16 v[56:59], v[148:151], v[160:163], v[56:59]
	v_mfma_f32_16x16x32_bf16 v[44:47], v[134:137], v[180:183], v[44:47]
	v_mfma_f32_16x16x32_bf16 v[40:43], v[148:151], v[180:183], v[40:43]
	v_mfma_f32_16x16x32_bf16 v[28:31], v[134:137], v[224:227], v[28:31]
	v_mfma_f32_16x16x32_bf16 v[24:27], v[148:151], v[224:227], v[24:27]
	v_mfma_f32_16x16x32_bf16 v[12:15], v[134:137], v[232:235], v[12:15]
	v_mfma_f32_16x16x32_bf16 v[8:11], v[148:151], v[232:235], v[8:11]
	s_barrier
	s_add_i32 m0, s59, 0x1c000
	s_add_u32 s52, s52, 0x40080
	s_addc_u32 s53, s53, 0
	global_load_lds_dwordx4 v0, s[52:53]
	s_add_i32 m0, s59, 0x1e000
	s_add_i32 s72, s72, 2
	global_load_lds_dwordx4 v2, s[52:53]
	s_add_u32 s70, s70, 0x100
	s_addc_u32 s71, s71, 0
	s_add_u32 s50, s50, 0x100
	s_addc_u32 s51, s51, 0
	s_cmp_gt_u32 s72, 13
	s_cbranch_scc1 .LrotX_848
	s_cmp_lg_u32 s72, 12
	s_cselect_b64 s[52:53], -1, 0
	s_add_u32 s26, s50, 0xfffc0080
	s_addc_u32 s54, s51, -1
	s_and_b64 s[52:53], s[52:53], exec
	s_cselect_b32 s55, s54, s25
	s_cselect_b32 s54, s26, s24
	s_cselect_b32 s53, s71, s14
	s_cselect_b32 s52, s70, s15
